# MLA k-loop rotated with barrier-phased halves (MFMA phase vs softmax phase), immediate pack, prefetch; diff loop as before
# baseline (speedup 1.0000x reference)
.LBB0_502:
	s_add_i32 s9, s36, 2
	s_add_i32 s13, s36, -1
	s_and_b32 s12, s13, 3
	s_add_i32 s0, s36, 1
	s_cmp_ge_u32 s0, s34
	s_cbranch_scc1 .Lmk_skip1
	s_add_i32 s0, s8, 0xc000
	s_and_b32 s0, s0, 0xc000
	s_add_i32 s0, s26, s0
	v_lshl_add_u64 v[198:199], s[84:85], 0, v[180:181]
	s_mov_b32 m0, s0
	v_lshl_add_u64 v[198:199], v[198:199], 0, s[16:17]
	global_load_lds_dwordx4 v[198:199], off
	v_lshl_add_u64 v[198:199], s[84:85], 0, v[178:179]
	s_add_i32 m0, s0, 0x2000
	v_lshl_add_u64 v[198:199], v[198:199], 0, s[16:17]
	global_load_lds_dwordx4 v[198:199], off

.Lmk_skip2:
	v_readlane_b32 s0, v252, 7
	s_cmpk_lt_u32 s0, 0x100
	s_cbranch_scc1 .Lmh0
	s_cmp_eq_u32 s36, 2
	s_cselect_b64 s[4:5], -1, 0
	s_mov_b64 s[10:11], 0

.Lmv_h1a_fast:
	v_add_f32_e32 v183, v183, v157
	v_lshl_add_u32 v0, s12, 14, v159
	s_add_i32 s0, s35, 0xffffc000
	s_and_b32 s0, s0, 0x4000
	v_add_u32_e32 v154, s0, v190
	v_add_u32_e32 v210, v0, v184
	v_add_u32_e32 v211, v0, v185
	v_add_u32_e32 v212, v0, v186
	v_add_u32_e32 v213, v0, v187
	v_add_u32_e32 v214, v0, v188
	v_add_u32_e32 v215, v0, v189
	v_add_u32_e32 v216, v154, v191
	v_add_u32_e32 v217, v154, v192
	v_add_u32_e32 v196, v154, v193
	v_add_u32_e32 v197, v154, v194
	ds_read_b128 v[98:101], v210
	ds_read_b128 v[102:105], v210 offset:8192
	ds_read_b128 v[106:109], v211
	ds_read_b128 v[110:113], v211 offset:8192
	s_barrier
	s_setprio 1
	s_waitcnt lgkmcnt(3)
	v_mfma_f32_32x32x16_bf16 v[66:81], v[98:101], v[114:117], v[34:49]
	ds_read_b128 v[98:101], v212
	s_waitcnt lgkmcnt(3)
	v_mfma_f32_32x32x16_bf16 v[50:65], v[102:105], v[114:117], v[34:49]
	ds_read_b128 v[102:105], v212 offset:8192
	s_waitcnt lgkmcnt(3)
	v_mfma_f32_32x32x16_bf16 v[66:81], v[106:109], v[118:121], v[66:81]
	ds_read_b128 v[106:109], v213
	s_waitcnt lgkmcnt(3)
	v_mfma_f32_32x32x16_bf16 v[50:65], v[110:113], v[118:121], v[50:65]
	ds_read_b128 v[110:113], v213 offset:8192
	s_waitcnt lgkmcnt(3)
	v_mfma_f32_32x32x16_bf16 v[66:81], v[98:101], v[122:125], v[66:81]
	ds_read_b128 v[98:101], v214
	s_waitcnt lgkmcnt(3)
	v_mfma_f32_32x32x16_bf16 v[50:65], v[102:105], v[122:125], v[50:65]
	ds_read_b128 v[102:105], v214 offset:8192
	s_waitcnt lgkmcnt(3)
	v_mfma_f32_32x32x16_bf16 v[66:81], v[106:109], v[126:129], v[66:81]
	ds_read_b128 v[106:109], v215
	s_waitcnt lgkmcnt(3)
	v_mfma_f32_32x32x16_bf16 v[50:65], v[110:113], v[126:129], v[50:65]
	ds_read_b128 v[110:113], v215 offset:8192
	s_waitcnt lgkmcnt(3)
	v_mfma_f32_32x32x16_bf16 v[66:81], v[98:101], v[130:133], v[66:81]
	ds_read_b128 v[98:101], v216
	s_waitcnt lgkmcnt(3)
	v_mfma_f32_32x32x16_bf16 v[50:65], v[102:105], v[130:133], v[50:65]
	ds_read_b128 v[102:105], v216 offset:4096
	s_waitcnt lgkmcnt(3)
	v_mfma_f32_32x32x16_bf16 v[66:81], v[106:109], v[134:137], v[66:81]
	ds_read_b128 v[106:109], v217
	s_waitcnt lgkmcnt(3)
	v_mfma_f32_32x32x16_bf16 v[50:65], v[110:113], v[134:137], v[50:65]
	ds_read_b128 v[110:113], v217 offset:4096
	s_waitcnt lgkmcnt(3)
	v_mfma_f32_32x32x16_bf16 v[2:17], v[98:101], v[82:85], v[2:17]
	ds_read_b128 v[98:101], v196
	s_waitcnt lgkmcnt(3)
	v_mfma_f32_32x32x16_bf16 v[18:33], v[102:105], v[82:85], v[18:33]
	ds_read_b128 v[102:105], v196 offset:4096
	s_waitcnt lgkmcnt(3)
	v_mfma_f32_32x32x16_bf16 v[2:17], v[106:109], v[86:89], v[2:17]
	ds_read_b128 v[106:109], v197
	s_waitcnt lgkmcnt(3)
	v_mfma_f32_32x32x16_bf16 v[18:33], v[110:113], v[86:89], v[18:33]
	ds_read_b128 v[110:113], v197 offset:4096
	s_waitcnt lgkmcnt(3)
	v_mfma_f32_32x32x16_bf16 v[2:17], v[98:101], v[90:93], v[2:17]
	s_waitcnt lgkmcnt(2)
	v_mfma_f32_32x32x16_bf16 v[18:33], v[102:105], v[90:93], v[18:33]
	s_waitcnt lgkmcnt(1)
	v_mfma_f32_32x32x16_bf16 v[2:17], v[106:109], v[94:97], v[2:17]
	s_waitcnt lgkmcnt(0)
	v_mfma_f32_32x32x16_bf16 v[18:33], v[110:113], v[94:97], v[18:33]
	s_setprio 0
	s_barrier
	s_cmp_ge_u32 s36, s34
	s_cbranch_scc1 .Lmv1_skip1
	s_and_b32 s0, s35, 0x4000
	s_add_i32 m0, s27, s0
	v_lshl_add_u64 v[198:199], s[84:85], 0, v[176:177]
	v_lshl_add_u64 v[198:199], v[198:199], 0, s[78:79]
	global_load_lds_dwordx4 v[198:199], off

.Lmv1_skip2:
	s_mov_b64 s[4:5], 0
	s_mov_b64 s[10:11], 0

.Lmv_h1b_fast:
	v_add_f32_e32 v183, v183, v157
	s_add_i32 s8, s8, 0x8000
	s_and_b32 s0, s8, 0x8000
	v_add_u32_e32 v0, s0, v159
	v_lshl_add_u32 v154, s12, 13, v190
	v_add_u32_e32 v210, v0, v184
	v_add_u32_e32 v211, v0, v185
	v_add_u32_e32 v212, v0, v186
	v_add_u32_e32 v213, v0, v187
	v_add_u32_e32 v214, v0, v188
	v_add_u32_e32 v215, v0, v189
	v_add_u32_e32 v216, v154, v191
	v_add_u32_e32 v217, v154, v192
	v_add_u32_e32 v196, v154, v193
	v_add_u32_e32 v197, v154, v194
	ds_read_b128 v[98:101], v210
	ds_read_b128 v[102:105], v210 offset:8192
	ds_read_b128 v[106:109], v211
	ds_read_b128 v[110:113], v211 offset:8192
	s_barrier
	s_setprio 1
	s_waitcnt lgkmcnt(3)
	v_mfma_f32_32x32x16_bf16 v[66:81], v[98:101], v[114:117], v[34:49]
	ds_read_b128 v[98:101], v212
	s_waitcnt lgkmcnt(3)
	v_mfma_f32_32x32x16_bf16 v[50:65], v[102:105], v[114:117], v[34:49]
	ds_read_b128 v[102:105], v212 offset:8192
	s_waitcnt lgkmcnt(3)
	v_mfma_f32_32x32x16_bf16 v[66:81], v[106:109], v[118:121], v[66:81]
	ds_read_b128 v[106:109], v213
	s_waitcnt lgkmcnt(3)
	v_mfma_f32_32x32x16_bf16 v[50:65], v[110:113], v[118:121], v[50:65]
	ds_read_b128 v[110:113], v213 offset:8192
	s_waitcnt lgkmcnt(3)
	v_mfma_f32_32x32x16_bf16 v[66:81], v[98:101], v[122:125], v[66:81]
	ds_read_b128 v[98:101], v214
	s_waitcnt lgkmcnt(3)
	v_mfma_f32_32x32x16_bf16 v[50:65], v[102:105], v[122:125], v[50:65]
	ds_read_b128 v[102:105], v214 offset:8192
	s_waitcnt lgkmcnt(3)
	v_mfma_f32_32x32x16_bf16 v[66:81], v[106:109], v[126:129], v[66:81]
	ds_read_b128 v[106:109], v215
	s_waitcnt lgkmcnt(3)
	v_mfma_f32_32x32x16_bf16 v[50:65], v[110:113], v[126:129], v[50:65]
	ds_read_b128 v[110:113], v215 offset:8192
	s_waitcnt lgkmcnt(3)
	v_mfma_f32_32x32x16_bf16 v[66:81], v[98:101], v[130:133], v[66:81]
	ds_read_b128 v[98:101], v216
	s_waitcnt lgkmcnt(3)
	v_mfma_f32_32x32x16_bf16 v[50:65], v[102:105], v[130:133], v[50:65]
	ds_read_b128 v[102:105], v216 offset:4096
	s_waitcnt lgkmcnt(3)
	v_mfma_f32_32x32x16_bf16 v[66:81], v[106:109], v[134:137], v[66:81]
	ds_read_b128 v[106:109], v217
	s_waitcnt lgkmcnt(3)
	v_mfma_f32_32x32x16_bf16 v[50:65], v[110:113], v[134:137], v[50:65]
	ds_read_b128 v[110:113], v217 offset:4096
	s_waitcnt lgkmcnt(3)
	v_mfma_f32_32x32x16_bf16 v[2:17], v[98:101], v[82:85], v[2:17]
	ds_read_b128 v[98:101], v196
	s_waitcnt lgkmcnt(3)
	v_mfma_f32_32x32x16_bf16 v[18:33], v[102:105], v[82:85], v[18:33]
	ds_read_b128 v[102:105], v196 offset:4096
	s_waitcnt lgkmcnt(3)
	v_mfma_f32_32x32x16_bf16 v[2:17], v[106:109], v[86:89], v[2:17]
	ds_read_b128 v[106:109], v197
	s_waitcnt lgkmcnt(3)
	v_mfma_f32_32x32x16_bf16 v[18:33], v[110:113], v[86:89], v[18:33]
	ds_read_b128 v[110:113], v197 offset:4096
	s_waitcnt lgkmcnt(3)
	v_mfma_f32_32x32x16_bf16 v[2:17], v[98:101], v[90:93], v[2:17]
	s_waitcnt lgkmcnt(2)
	v_mfma_f32_32x32x16_bf16 v[18:33], v[102:105], v[90:93], v[18:33]
	s_waitcnt lgkmcnt(1)
	v_mfma_f32_32x32x16_bf16 v[2:17], v[106:109], v[94:97], v[2:17]
	s_waitcnt lgkmcnt(0)
	v_mfma_f32_32x32x16_bf16 v[18:33], v[110:113], v[94:97], v[18:33]
	s_setprio 0
	s_branch .Lmjoin
.Lmh0:
	v_lshl_add_u32 v0, s12, 14, v159
	s_add_i32 s0, s35, 0xffffc000
	s_and_b32 s0, s0, 0x4000
	v_add_u32_e32 v154, s0, v190
	v_add_u32_e32 v210, v0, v184
	v_add_u32_e32 v211, v0, v185
	v_add_u32_e32 v212, v0, v186
	v_add_u32_e32 v213, v0, v187
	v_add_u32_e32 v214, v0, v188
	v_add_u32_e32 v215, v0, v189
	v_add_u32_e32 v216, v154, v191
	v_add_u32_e32 v217, v154, v192
	v_add_u32_e32 v196, v154, v193
	v_add_u32_e32 v197, v154, v194
	ds_read_b128 v[98:101], v210
	ds_read_b128 v[102:105], v210 offset:8192
	ds_read_b128 v[106:109], v211
	ds_read_b128 v[110:113], v211 offset:8192
	s_setprio 1
	s_waitcnt lgkmcnt(3)
	v_mfma_f32_32x32x16_bf16 v[66:81], v[98:101], v[114:117], v[34:49]
	ds_read_b128 v[98:101], v212
	s_waitcnt lgkmcnt(3)
	v_mfma_f32_32x32x16_bf16 v[50:65], v[102:105], v[114:117], v[34:49]
	ds_read_b128 v[102:105], v212 offset:8192
	s_waitcnt lgkmcnt(3)
	v_mfma_f32_32x32x16_bf16 v[66:81], v[106:109], v[118:121], v[66:81]
	ds_read_b128 v[106:109], v213
	s_waitcnt lgkmcnt(3)
	v_mfma_f32_32x32x16_bf16 v[50:65], v[110:113], v[118:121], v[50:65]
	ds_read_b128 v[110:113], v213 offset:8192
	s_waitcnt lgkmcnt(3)
	v_mfma_f32_32x32x16_bf16 v[66:81], v[98:101], v[122:125], v[66:81]
	ds_read_b128 v[98:101], v214
	s_waitcnt lgkmcnt(3)
	v_mfma_f32_32x32x16_bf16 v[50:65], v[102:105], v[122:125], v[50:65]
	ds_read_b128 v[102:105], v214 offset:8192
	s_waitcnt lgkmcnt(3)
	v_mfma_f32_32x32x16_bf16 v[66:81], v[106:109], v[126:129], v[66:81]
	ds_read_b128 v[106:109], v215
	s_waitcnt lgkmcnt(3)
	v_mfma_f32_32x32x16_bf16 v[50:65], v[110:113], v[126:129], v[50:65]
	ds_read_b128 v[110:113], v215 offset:8192
	s_waitcnt lgkmcnt(3)
	v_mfma_f32_32x32x16_bf16 v[66:81], v[98:101], v[130:133], v[66:81]
	ds_read_b128 v[98:101], v216
	s_waitcnt lgkmcnt(3)
	v_mfma_f32_32x32x16_bf16 v[50:65], v[102:105], v[130:133], v[50:65]
	ds_read_b128 v[102:105], v216 offset:4096
	s_waitcnt lgkmcnt(3)
	v_mfma_f32_32x32x16_bf16 v[66:81], v[106:109], v[134:137], v[66:81]
	ds_read_b128 v[106:109], v217
	s_waitcnt lgkmcnt(3)
	v_mfma_f32_32x32x16_bf16 v[50:65], v[110:113], v[134:137], v[50:65]
	ds_read_b128 v[110:113], v217 offset:4096
	s_waitcnt lgkmcnt(3)
	v_mfma_f32_32x32x16_bf16 v[2:17], v[98:101], v[82:85], v[2:17]
	ds_read_b128 v[98:101], v196
	s_waitcnt lgkmcnt(3)
	v_mfma_f32_32x32x16_bf16 v[18:33], v[102:105], v[82:85], v[18:33]
	ds_read_b128 v[102:105], v196 offset:4096
	s_waitcnt lgkmcnt(3)
	v_mfma_f32_32x32x16_bf16 v[2:17], v[106:109], v[86:89], v[2:17]
	ds_read_b128 v[106:109], v197
	s_waitcnt lgkmcnt(3)
	v_mfma_f32_32x32x16_bf16 v[18:33], v[110:113], v[86:89], v[18:33]
	ds_read_b128 v[110:113], v197 offset:4096
	s_waitcnt lgkmcnt(3)
	v_mfma_f32_32x32x16_bf16 v[2:17], v[98:101], v[90:93], v[2:17]
	s_waitcnt lgkmcnt(2)
	v_mfma_f32_32x32x16_bf16 v[18:33], v[102:105], v[90:93], v[18:33]
	s_waitcnt lgkmcnt(1)
	v_mfma_f32_32x32x16_bf16 v[2:17], v[106:109], v[94:97], v[2:17]
	s_waitcnt lgkmcnt(0)
	v_mfma_f32_32x32x16_bf16 v[18:33], v[110:113], v[94:97], v[18:33]
	s_setprio 0
	s_barrier
	s_cmp_ge_u32 s36, s34
	s_cbranch_scc1 .Lmv_skip1
	s_and_b32 s0, s35, 0x4000
	s_add_i32 m0, s27, s0
	v_lshl_add_u64 v[198:199], s[84:85], 0, v[176:177]
	v_lshl_add_u64 v[198:199], v[198:199], 0, s[78:79]
	global_load_lds_dwordx4 v[198:199], off

.Lmv_h0a_fast:
	v_add_f32_e32 v183, v183, v157
	s_add_i32 s8, s8, 0x8000
	s_and_b32 s0, s8, 0x8000
	v_add_u32_e32 v0, s0, v159
	v_lshl_add_u32 v154, s12, 13, v190
	v_add_u32_e32 v210, v0, v184
	v_add_u32_e32 v211, v0, v185
	v_add_u32_e32 v212, v0, v186
	v_add_u32_e32 v213, v0, v187
	v_add_u32_e32 v214, v0, v188
	v_add_u32_e32 v215, v0, v189
	v_add_u32_e32 v216, v154, v191
	v_add_u32_e32 v217, v154, v192
	v_add_u32_e32 v196, v154, v193
	v_add_u32_e32 v197, v154, v194
	ds_read_b128 v[98:101], v210
	ds_read_b128 v[102:105], v210 offset:8192
	ds_read_b128 v[106:109], v211
	ds_read_b128 v[110:113], v211 offset:8192
	s_barrier
	s_setprio 1
	s_waitcnt lgkmcnt(3)
	v_mfma_f32_32x32x16_bf16 v[66:81], v[98:101], v[114:117], v[34:49]
	ds_read_b128 v[98:101], v212
	s_waitcnt lgkmcnt(3)
	v_mfma_f32_32x32x16_bf16 v[50:65], v[102:105], v[114:117], v[34:49]
	ds_read_b128 v[102:105], v212 offset:8192
	s_waitcnt lgkmcnt(3)
	v_mfma_f32_32x32x16_bf16 v[66:81], v[106:109], v[118:121], v[66:81]
	ds_read_b128 v[106:109], v213
	s_waitcnt lgkmcnt(3)
	v_mfma_f32_32x32x16_bf16 v[50:65], v[110:113], v[118:121], v[50:65]
	ds_read_b128 v[110:113], v213 offset:8192
	s_waitcnt lgkmcnt(3)
	v_mfma_f32_32x32x16_bf16 v[66:81], v[98:101], v[122:125], v[66:81]
	ds_read_b128 v[98:101], v214
	s_waitcnt lgkmcnt(3)
	v_mfma_f32_32x32x16_bf16 v[50:65], v[102:105], v[122:125], v[50:65]
	ds_read_b128 v[102:105], v214 offset:8192
	s_waitcnt lgkmcnt(3)
	v_mfma_f32_32x32x16_bf16 v[66:81], v[106:109], v[126:129], v[66:81]
	ds_read_b128 v[106:109], v215
	s_waitcnt lgkmcnt(3)
	v_mfma_f32_32x32x16_bf16 v[50:65], v[110:113], v[126:129], v[50:65]
	ds_read_b128 v[110:113], v215 offset:8192
	s_waitcnt lgkmcnt(3)
	v_mfma_f32_32x32x16_bf16 v[66:81], v[98:101], v[130:133], v[66:81]
	ds_read_b128 v[98:101], v216
	s_waitcnt lgkmcnt(3)
	v_mfma_f32_32x32x16_bf16 v[50:65], v[102:105], v[130:133], v[50:65]
	ds_read_b128 v[102:105], v216 offset:4096
	s_waitcnt lgkmcnt(3)
	v_mfma_f32_32x32x16_bf16 v[66:81], v[106:109], v[134:137], v[66:81]
	ds_read_b128 v[106:109], v217
	s_waitcnt lgkmcnt(3)
	v_mfma_f32_32x32x16_bf16 v[50:65], v[110:113], v[134:137], v[50:65]
	ds_read_b128 v[110:113], v217 offset:4096
	s_waitcnt lgkmcnt(3)
	v_mfma_f32_32x32x16_bf16 v[2:17], v[98:101], v[82:85], v[2:17]
	ds_read_b128 v[98:101], v196
	s_waitcnt lgkmcnt(3)
	v_mfma_f32_32x32x16_bf16 v[18:33], v[102:105], v[82:85], v[18:33]
	ds_read_b128 v[102:105], v196 offset:4096
	s_waitcnt lgkmcnt(3)
	v_mfma_f32_32x32x16_bf16 v[2:17], v[106:109], v[86:89], v[2:17]
	ds_read_b128 v[106:109], v197
	s_waitcnt lgkmcnt(3)
	v_mfma_f32_32x32x16_bf16 v[18:33], v[110:113], v[86:89], v[18:33]
	ds_read_b128 v[110:113], v197 offset:4096
	s_waitcnt lgkmcnt(3)
	v_mfma_f32_32x32x16_bf16 v[2:17], v[98:101], v[90:93], v[2:17]
	s_waitcnt lgkmcnt(2)
	v_mfma_f32_32x32x16_bf16 v[18:33], v[102:105], v[90:93], v[18:33]
	s_waitcnt lgkmcnt(1)
	v_mfma_f32_32x32x16_bf16 v[2:17], v[106:109], v[94:97], v[2:17]
	s_waitcnt lgkmcnt(0)
	v_mfma_f32_32x32x16_bf16 v[18:33], v[110:113], v[94:97], v[18:33]
	s_setprio 0
	s_barrier
	s_cmp_ge_u32 s36, s34
	s_cbranch_scc1 .Lmjoin
	s_mov_b64 s[4:5], 0
	s_mov_b64 s[10:11], 0
